# v38 + closed-form tile index (pm,pn) in the unit loops of the seven M=16384 StaticOrder GEMMs (replaces ~55-op generic division chain per tile)
# baseline (speedup 1.0000x reference)
;     __host__ __device__ bool next(int i, Unit& u) const {
;         const long L = (long)i * G + c; if (L >= nwg) return false;
;         int wgid = (int)L; { const int q = nwg / NXCD, r = nwg % NXCD, xcd = wgid % NXCD, off = wgid / NXCD; wgid = (xcd < r ? xcd * (q + 1) : r * (q + 1) + (xcd - r) * q) + off; }
;         const int nig = WGM * nN, gid = wgid / nig, fm = gid * WGM, gsz = (nM - fm) < WGM ? (nM - fm) : WGM;
;         u.pm = fm + ((wgid % nig) % gsz); u.pn = (wgid % nig) / gsz; return true;
; template <class Epi, class Sched, bool ALIGN_EPI = false, bool SP2 = false>
; __device__ __forceinline__ void gemm_phase(PG8_LAS unsigned char* lds, const Gemm g, const Sched& S, const Epi& E) {
;     ...
;         const bool has_next = S.next(ui + 1, nxt);
.LBB0_222:
	s_add_i32 s21, s21, 1
	s_mul_i32 s0, s21, s25
	s_mul_hi_u32 s1, s21, s10
	s_add_i32 s1, s1, s0
	s_mul_i32 s0, s21, s10
	s_add_u32 s2, s0, s76
	s_addc_u32 s3, s1, s7
	v_cmp_gt_i64_e32 vcc, s[2:3], v[144:145]
	v_cmp_lt_i64_e64 s[0:1], s[2:3], v[142:143]
	s_cbranch_vccnz .LBB0_228
	s_and_b32 s48, s2, 7
	s_lshl_b32 s48, s48, 3
	s_bfe_u32 s3, s2, 0x30003
	s_or_b32 s48, s48, s3
	s_lshr_b32 s44, s2, 6

;     __host__ __device__ bool next(int i, Unit& u) const {
;         const long L = (long)i * G + c; if (L >= nwg) return false;
;         int wgid = (int)L; { const int q = nwg / NXCD, r = nwg % NXCD, xcd = wgid % NXCD, off = wgid / NXCD; wgid = (xcd < r ? xcd * (q + 1) : r * (q + 1) + (xcd - r) * q) + off; }
;         const int nig = WGM * nN, gid = wgid / nig, fm = gid * WGM, gsz = (nM - fm) < WGM ? (nM - fm) : WGM;
;         u.pm = fm + ((wgid % nig) % gsz); u.pn = (wgid % nig) / gsz; return true;
; template <class Epi, class Sched, bool ALIGN_EPI = false, bool SP2 = false>
; __device__ __forceinline__ void gemm_phase(PG8_LAS unsigned char* lds, const Gemm g, const Sched& S, const Epi& E) {
;     ...
;         const bool has_next = S.next(ui + 1, nxt);
.LBB0_244:
	s_add_i32 s29, s35, 1
	s_mul_i32 s0, s29, s26
	s_mul_hi_u32 s1, s29, s10
	s_add_i32 s1, s1, s0
	s_mul_i32 s0, s29, s10
	s_add_u32 s4, s0, s76
	s_addc_u32 s5, s1, s8
	v_cmp_gt_i64_e32 vcc, s[4:5], v[164:165]
	v_cmp_lt_i64_e64 s[0:1], s[4:5], v[162:163]
	s_cbranch_vccnz .LBB0_246
	s_and_b32 s62, s4, 7
	s_lshl_b32 s62, s62, 3
	s_bfe_u32 s5, s4, 0x30003
	s_or_b32 s62, s62, s5
	s_lshr_b32 s58, s4, 6

;     __host__ __device__ bool next(int i, Unit& u) const {
;         const long L = (long)i * G + c; if (L >= nwg) return false;
;         int wgid = (int)L; { const int q = nwg / NXCD, r = nwg % NXCD, xcd = wgid % NXCD, off = wgid / NXCD; wgid = (xcd < r ? xcd * (q + 1) : r * (q + 1) + (xcd - r) * q) + off; }
;         const int nig = WGM * nN, gid = wgid / nig, fm = gid * WGM, gsz = (nM - fm) < WGM ? (nM - fm) : WGM;
;         u.pm = fm + ((wgid % nig) % gsz); u.pn = (wgid % nig) / gsz; return true;
; template <class Epi, class Sched, bool ALIGN_EPI = false, bool SP2 = false>
; __device__ __forceinline__ void gemm_phase(PG8_LAS unsigned char* lds, const Gemm g, const Sched& S, const Epi& E) {
;     ...
;         const bool has_next = S.next(ui + 1, nxt);
.LBB0_266:
	s_add_i32 s33, s36, 1
	s_mul_i32 s0, s33, s27
	s_mul_hi_u32 s1, s33, s10
	s_add_i32 s1, s1, s0
	s_mul_i32 s0, s33, s10
	s_add_u32 s4, s0, s76
	s_addc_u32 s5, s1, s7
	v_cmp_gt_i64_e32 vcc, s[4:5], v[164:165]
	v_cmp_lt_i64_e64 s[0:1], s[4:5], v[162:163]
	s_cbranch_vccnz .LBB0_272
	s_and_b32 s48, s4, 7
	s_lshl_b32 s48, s48, 3
	s_bfe_u32 s5, s4, 0x30003
	s_or_b32 s48, s48, s5
	s_lshr_b32 s38, s4, 6

;     __host__ __device__ bool next(int i, Unit& u) const {
;         const long L = (long)i * G + c; if (L >= nwg) return false;
;         int wgid = (int)L; { const int q = nwg / NXCD, r = nwg % NXCD, xcd = wgid % NXCD, off = wgid / NXCD; wgid = (xcd < r ? xcd * (q + 1) : r * (q + 1) + (xcd - r) * q) + off; }
;         const int nig = WGM * nN, gid = wgid / nig, fm = gid * WGM, gsz = (nM - fm) < WGM ? (nM - fm) : WGM;
;         u.pm = fm + ((wgid % nig) % gsz); u.pn = (wgid % nig) / gsz; return true;
; template <class Epi, class Sched, bool ALIGN_EPI = false, bool SP2 = false>
; __device__ __forceinline__ void gemm_phase(PG8_LAS unsigned char* lds, const Gemm g, const Sched& S, const Epi& E) {
;     ...
;         const bool has_next = S.next(ui + 1, nxt);
.LBB0_548:
	s_add_i32 s25, s26, 1
	s_mul_i32 s1, s25, s22
	s_mul_hi_u32 s4, s25, s10
	s_add_i32 s4, s4, s1
	s_mul_i32 s1, s25, s10
	s_add_u32 s56, s1, s76
	s_addc_u32 s57, s4, s6
	v_cmp_gt_i64_e32 vcc, s[56:57], v[184:185]
	v_cmp_lt_i64_e64 s[4:5], s[56:57], v[182:183]
	s_cbranch_vccnz .LBB0_554
	s_and_b32 s54, s56, 7
	s_lshl_b32 s54, s54, 3
	s_bfe_u32 s28, s56, 0x30003
	s_or_b32 s54, s54, s28
	s_lshr_b32 s0, s56, 6

;     __host__ __device__ bool next(int i, Unit& u) const {
;         const long L = (long)i * G + c; if (L >= nwg) return false;
;         int wgid = (int)L; { const int q = nwg / NXCD, r = nwg % NXCD, xcd = wgid % NXCD, off = wgid / NXCD; wgid = (xcd < r ? xcd * (q + 1) : r * (q + 1) + (xcd - r) * q) + off; }
;         const int nig = WGM * nN, gid = wgid / nig, fm = gid * WGM, gsz = (nM - fm) < WGM ? (nM - fm) : WGM;
;         u.pm = fm + ((wgid % nig) % gsz); u.pn = (wgid % nig) / gsz; return true;
; template <class Epi, class Sched, bool ALIGN_EPI = false, bool SP2 = false>
; __device__ __forceinline__ void gemm_phase(PG8_LAS unsigned char* lds, const Gemm g, const Sched& S, const Epi& E) {
;     ...
;         const bool has_next = S.next(ui + 1, nxt);
.LBB0_572:
	s_add_i32 s16, s16, 1
	s_mul_i32 s2, s16, s20
	s_mul_hi_u32 s3, s16, s10
	s_add_i32 s3, s3, s2
	s_mul_i32 s2, s16, s10
	s_add_u32 s50, s2, s76
	s_addc_u32 s51, s3, s6
	v_cmp_gt_i64_e32 vcc, s[50:51], v[196:197]
	v_cmp_lt_i64_e64 s[2:3], s[50:51], v[194:195]
	s_cbranch_vccnz .LBB0_578
	s_and_b32 s48, s50, 7
	s_lshl_b32 s48, s48, 3
	s_bfe_u32 s24, s50, 0x30003
	s_or_b32 s48, s48, s24
	s_lshr_b32 s42, s50, 6

;     __host__ __device__ bool next(int i, Unit& u) const {
;         const long L = (long)i * G + c; if (L >= nwg) return false;
;         int wgid = (int)L; { const int q = nwg / NXCD, r = nwg % NXCD, xcd = wgid % NXCD, off = wgid / NXCD; wgid = (xcd < r ? xcd * (q + 1) : r * (q + 1) + (xcd - r) * q) + off; }
;         const int nig = WGM * nN, gid = wgid / nig, fm = gid * WGM, gsz = (nM - fm) < WGM ? (nM - fm) : WGM;
;         u.pm = fm + ((wgid % nig) % gsz); u.pn = (wgid % nig) / gsz; return true;
; template <class Epi, class Sched, bool ALIGN_EPI = false, bool SP2 = false>
; __device__ __forceinline__ void gemm_phase(PG8_LAS unsigned char* lds, const Gemm g, const Sched& S, const Epi& E) {
;     ...
;         const bool has_next = S.next(ui + 1, nxt);
.LBB0_651:
	s_add_i32 s16, s16, 1
	s_mul_i32 s0, s16, s19
	s_mul_hi_u32 s1, s16, s10
	s_add_i32 s1, s1, s0
	s_mul_i32 s0, s16, s10
	s_add_u32 s2, s0, s76
	s_addc_u32 s3, s1, s6
	v_cmp_gt_i64_e32 vcc, s[2:3], v[144:145]
	v_cmp_lt_i64_e64 s[0:1], s[2:3], v[142:143]
	s_cbranch_vccnz .LBB0_657
	s_and_b32 s56, s2, 7
	s_lshl_b32 s56, s56, 3
	s_bfe_u32 s3, s2, 0x30003
	s_or_b32 s56, s56, s3
	s_lshr_b32 s54, s2, 6

;     __host__ __device__ bool next(int i, Unit& u) const {
;         const long L = (long)i * G + c; if (L >= nwg) return false;
;         int wgid = (int)L; { const int q = nwg / NXCD, r = nwg % NXCD, xcd = wgid % NXCD, off = wgid / NXCD; wgid = (xcd < r ? xcd * (q + 1) : r * (q + 1) + (xcd - r) * q) + off; }
;         const int nig = WGM * nN, gid = wgid / nig, fm = gid * WGM, gsz = (nM - fm) < WGM ? (nM - fm) : WGM;
;         u.pm = fm + ((wgid % nig) % gsz); u.pn = (wgid % nig) / gsz; return true;
; template <class Epi, class Sched, bool ALIGN_EPI = false, bool SP2 = false>
; __device__ __forceinline__ void gemm_phase(PG8_LAS unsigned char* lds, const Gemm g, const Sched& S, const Epi& E) {
;     ...
;         const bool has_next = S.next(ui + 1, nxt);
.LBB0_838:
	s_add_i32 s33, s55, 1
	s_mul_i32 s4, s33, s26
	s_mul_hi_u32 s5, s33, s10
	s_add_i32 s5, s5, s4
	s_mul_i32 s4, s33, s10
	s_add_u32 s50, s4, s76
	s_addc_u32 s51, s5, s7
	v_cmp_gt_i64_e32 vcc, s[50:51], v[164:165]
	v_cmp_lt_i64_e64 s[4:5], s[50:51], v[162:163]
	s_cbranch_vccnz .LBB0_840
	s_and_b32 s48, s50, 7
	s_lshl_b32 s48, s48, 3
	s_bfe_u32 s47, s50, 0x30003
	s_or_b32 s48, s48, s47
	s_lshr_b32 s46, s50, 6
